# grid-barrier seams: non-leader workgroups poll the cross-XCC release generation directly (one forwarding hop less)
# speedup vs baseline: 1.0259x; 1.0064x over previous
; __device__ __forceinline__ unsigned xb_ld(unsigned* p)              { return __hip_atomic_load(p, __ATOMIC_RELAXED, __HIP_MEMORY_SCOPE_AGENT); }
; __device__ __forceinline__ unsigned xb_add(unsigned* p, unsigned v) { return __hip_atomic_fetch_add(p, v, __ATOMIC_RELAXED, __HIP_MEMORY_SCOPE_AGENT); }
; #define XB_SPIN(cond, bar) do { unsigned _sp = 0; while (cond) { __builtin_amdgcn_s_sleep(1); \
;     if ((++_sp & 255u) == 0u) { if (xb_ld(&(bar)[XB_TMO])) break; if (_sp > XB_SPIN_CAP) { atomicAdd(&(bar)[XB_TMO], 1u); break; } } } } while (0)
; __device__ __forceinline__ void xcd_barrier(const XcdBarrier& b) {
;     ...
;         const unsigned old = xb_add(&bar[XB_XSUB(b.x)], 1u);
;         const unsigned gen = old / nloc;
;         if (old + 1u == (gen + 1u) * nloc) {
;             __builtin_amdgcn_fence(__ATOMIC_RELEASE, "agent");
;             asm volatile("s_waitcnt vmcnt(0)" ::: "memory");
;             const unsigned og = xb_add(&bar[XB_TOP], 1u);
;             const unsigned tg = og / nx;
;             if (og + 1u == (tg + 1u) * nx) xb_add(&bar[XB_TOPGEN], 1u);
;             else XB_SPIN(xb_ld(&bar[XB_TOPGEN]) == tg, bar);
;             __builtin_amdgcn_fence(__ATOMIC_ACQUIRE, "agent");
;             xb_add(&bar[XB_XGEN(b.x)], 1u);
;             asm volatile("s_waitcnt vmcnt(0)" ::: "memory");
;         } else {
;             XB_SPIN(xb_ld(&bar[XB_XGEN(b.x)]) == gen, bar);
.LBB0_69:
	s_or_b64 exec, exec, s[8:9]
	v_cvt_f32_u32_e32 v6, v4
	s_waitcnt vmcnt(0)
	v_readfirstlane_b32 s2, v5
	v_sub_u32_e32 v5, 0, v4
	v_rcp_iflag_f32_e32 v6, v6
	v_add_u32_e32 v7, s2, v3
	v_mul_f32_e32 v6, 0x4f7ffffe, v6
	v_cvt_u32_f32_e32 v6, v6
	v_mul_lo_u32 v3, v5, v6
	v_mul_hi_u32 v3, v6, v3
	v_add_u32_e32 v3, v6, v3
	v_mul_hi_u32 v3, v7, v3
	v_mul_lo_u32 v5, v3, v4
	v_sub_u32_e32 v5, v7, v5
	v_add_u32_e32 v6, 1, v3
	v_cmp_ge_u32_e32 vcc, v5, v4
	s_nop 1
	v_cndmask_b32_e32 v3, v3, v6, vcc
	v_sub_u32_e32 v6, v5, v4
	v_cndmask_b32_e32 v5, v5, v6, vcc
	v_add_u32_e32 v6, 1, v3
	v_cmp_ge_u32_e32 vcc, v5, v4
	v_add_u32_e32 v5, 1, v7
	s_nop 0
	v_cndmask_b32_e32 v3, v3, v6, vcc
	v_mul_lo_u32 v6, v4, v3
	v_add_u32_e32 v4, v6, v4
	v_cmp_ne_u32_e32 vcc, v5, v4
	s_and_saveexec_b64 s[2:3], vcc
	s_xor_b64 s[6:7], exec, s[2:3]
	s_cbranch_execz .LBB0_83
	s_waitcnt lgkmcnt(0)
	buffer_inv sc1
	v_readlane_b32 s12, v239, 3
	v_readlane_b32 s13, v239, 4
	v_mov_b32_e32 v2, 0
	s_nop 1
	s_add_u32 s12, s12, 0x23500
	s_addc_u32 s13, s13, 0
	global_load_dword v2, v2, s[12:13] sc1
	s_waitcnt vmcnt(0)
	v_cmp_eq_u32_e32 vcc, v2, v3
	s_and_saveexec_b64 s[8:9], vcc
	s_cbranch_execz .LBB0_82
	v_readlane_b32 s16, v239, 1
	v_readlane_b32 s18, v239, 3
	v_readlane_b32 s19, v239, 4
	s_add_u32 s10, s18, 0x20200
	v_readlane_b32 s17, v239, 2
	s_addc_u32 s11, s19, 0
	s_mov_b32 s2, 1
	s_mov_b64 s[14:15], 0
	v_mov_b32_e32 v2, 0
	s_branch .LBB0_73

; __device__ __forceinline__ unsigned xb_ld(unsigned* p)              { return __hip_atomic_load(p, __ATOMIC_RELAXED, __HIP_MEMORY_SCOPE_AGENT); }
; __device__ __forceinline__ unsigned xb_add(unsigned* p, unsigned v) { return __hip_atomic_fetch_add(p, v, __ATOMIC_RELAXED, __HIP_MEMORY_SCOPE_AGENT); }
; #define XB_SPIN(cond, bar) do { unsigned _sp = 0; while (cond) { __builtin_amdgcn_s_sleep(1); \
;     if ((++_sp & 255u) == 0u) { if (xb_ld(&(bar)[XB_TMO])) break; if (_sp > XB_SPIN_CAP) { atomicAdd(&(bar)[XB_TMO], 1u); break; } } } } while (0)
; __device__ __forceinline__ void xcd_barrier(const XcdBarrier& b) {
;     ...
;         const unsigned old = xb_add(&bar[XB_XSUB(b.x)], 1u);
;         const unsigned gen = old / nloc;
;         if (old + 1u == (gen + 1u) * nloc) {
;             __builtin_amdgcn_fence(__ATOMIC_RELEASE, "agent");
;             asm volatile("s_waitcnt vmcnt(0)" ::: "memory");
;             const unsigned og = xb_add(&bar[XB_TOP], 1u);
;             const unsigned tg = og / nx;
;             if (og + 1u == (tg + 1u) * nx) xb_add(&bar[XB_TOPGEN], 1u);
;             else XB_SPIN(xb_ld(&bar[XB_TOPGEN]) == tg, bar);
;             __builtin_amdgcn_fence(__ATOMIC_ACQUIRE, "agent");
;             xb_add(&bar[XB_XGEN(b.x)], 1u);
;             asm volatile("s_waitcnt vmcnt(0)" ::: "memory");
;         } else {
;             XB_SPIN(xb_ld(&bar[XB_XGEN(b.x)]) == gen, bar);
.LBB0_825:
	s_or_b64 exec, exec, s[10:11]
	v_cvt_f32_u32_e32 v5, v3
	s_waitcnt vmcnt(0)
	v_readfirstlane_b32 s2, v4
	v_sub_u32_e32 v4, 0, v3
	v_rcp_iflag_f32_e32 v5, v5
	v_add_u32_e32 v6, s2, v2
	v_mul_f32_e32 v5, 0x4f7ffffe, v5
	v_cvt_u32_f32_e32 v5, v5
	v_mul_lo_u32 v2, v4, v5
	v_mul_hi_u32 v2, v5, v2
	v_add_u32_e32 v2, v5, v2
	v_mul_hi_u32 v2, v6, v2
	v_mul_lo_u32 v4, v2, v3
	v_sub_u32_e32 v4, v6, v4
	v_add_u32_e32 v5, 1, v2
	v_cmp_ge_u32_e32 vcc, v4, v3
	s_nop 1
	v_cndmask_b32_e32 v2, v2, v5, vcc
	v_sub_u32_e32 v5, v4, v3
	v_cndmask_b32_e32 v4, v4, v5, vcc
	v_add_u32_e32 v5, 1, v2
	v_cmp_ge_u32_e32 vcc, v4, v3
	v_add_u32_e32 v4, 1, v6
	s_nop 0
	v_cndmask_b32_e32 v2, v2, v5, vcc
	v_mul_lo_u32 v5, v3, v2
	v_add_u32_e32 v3, v5, v3
	v_cmp_ne_u32_e32 vcc, v4, v3
	s_and_saveexec_b64 s[2:3], vcc
	s_xor_b64 s[6:7], exec, s[2:3]
	s_cbranch_execz .LBB0_839
	s_waitcnt lgkmcnt(0)
	buffer_inv sc1
	v_readlane_b32 s14, v239, 3
	v_readlane_b32 s15, v239, 4
	v_mov_b32_e32 v1, 0
	s_nop 1
	s_add_u32 s14, s14, 0x23500
	s_addc_u32 s15, s15, 0
	global_load_dword v1, v1, s[14:15] sc1
	s_waitcnt vmcnt(0)
	v_cmp_eq_u32_e32 vcc, v1, v2
	s_and_saveexec_b64 s[10:11], vcc
	s_cbranch_execz .LBB0_838
	v_readlane_b32 s16, v239, 1
	v_readlane_b32 s18, v239, 3
	v_readlane_b32 s17, v239, 2
	v_readlane_b32 s19, v239, 4
	s_add_u32 s12, s18, 0x20200
	s_addc_u32 s13, s19, 0
	s_mov_b32 s2, 1
	s_mov_b64 s[16:17], 0
	v_mov_b32_e32 v1, 0
	s_branch .LBB0_829

; __device__ __forceinline__ unsigned xb_ld(unsigned* p)              { return __hip_atomic_load(p, __ATOMIC_RELAXED, __HIP_MEMORY_SCOPE_AGENT); }
; __device__ __forceinline__ unsigned xb_add(unsigned* p, unsigned v) { return __hip_atomic_fetch_add(p, v, __ATOMIC_RELAXED, __HIP_MEMORY_SCOPE_AGENT); }
; #define XB_SPIN(cond, bar) do { unsigned _sp = 0; while (cond) { __builtin_amdgcn_s_sleep(1); \
;     if ((++_sp & 255u) == 0u) { if (xb_ld(&(bar)[XB_TMO])) break; if (_sp > XB_SPIN_CAP) { atomicAdd(&(bar)[XB_TMO], 1u); break; } } } } while (0)
; __device__ __forceinline__ void xcd_barrier(const XcdBarrier& b) {
;     ...
;         const unsigned old = xb_add(&bar[XB_XSUB(b.x)], 1u);
;         const unsigned gen = old / nloc;
;         if (old + 1u == (gen + 1u) * nloc) {
;             __builtin_amdgcn_fence(__ATOMIC_RELEASE, "agent");
;             asm volatile("s_waitcnt vmcnt(0)" ::: "memory");
;             const unsigned og = xb_add(&bar[XB_TOP], 1u);
;             const unsigned tg = og / nx;
;             if (og + 1u == (tg + 1u) * nx) xb_add(&bar[XB_TOPGEN], 1u);
;             else XB_SPIN(xb_ld(&bar[XB_TOPGEN]) == tg, bar);
;             __builtin_amdgcn_fence(__ATOMIC_ACQUIRE, "agent");
;             xb_add(&bar[XB_XGEN(b.x)], 1u);
;             asm volatile("s_waitcnt vmcnt(0)" ::: "memory");
;         } else {
;             XB_SPIN(xb_ld(&bar[XB_XGEN(b.x)]) == gen, bar);
.LBB0_939:
	s_or_b64 exec, exec, s[12:13]
	v_cvt_f32_u32_e32 v5, v3
	s_waitcnt vmcnt(0)
	v_readfirstlane_b32 s2, v4
	v_sub_u32_e32 v4, 0, v3
	v_rcp_iflag_f32_e32 v5, v5
	v_add_u32_e32 v6, s2, v2
	v_mul_f32_e32 v5, 0x4f7ffffe, v5
	v_cvt_u32_f32_e32 v5, v5
	v_mul_lo_u32 v2, v4, v5
	v_mul_hi_u32 v2, v5, v2
	v_add_u32_e32 v2, v5, v2
	v_mul_hi_u32 v2, v6, v2
	v_mul_lo_u32 v4, v2, v3
	v_sub_u32_e32 v4, v6, v4
	v_add_u32_e32 v5, 1, v2
	v_cmp_ge_u32_e32 vcc, v4, v3
	s_nop 1
	v_cndmask_b32_e32 v2, v2, v5, vcc
	v_sub_u32_e32 v5, v4, v3
	v_cndmask_b32_e32 v4, v4, v5, vcc
	v_add_u32_e32 v5, 1, v2
	v_cmp_ge_u32_e32 vcc, v4, v3
	v_add_u32_e32 v4, 1, v6
	s_nop 0
	v_cndmask_b32_e32 v2, v2, v5, vcc
	v_mul_lo_u32 v5, v3, v2
	v_add_u32_e32 v3, v5, v3
	v_cmp_ne_u32_e32 vcc, v4, v3
	s_and_saveexec_b64 s[2:3], vcc
	s_xor_b64 s[6:7], exec, s[2:3]
	s_cbranch_execz .LBB0_953
	s_waitcnt lgkmcnt(0)
	buffer_inv sc1
	v_readlane_b32 s16, v239, 3
	v_readlane_b32 s17, v239, 4
	v_mov_b32_e32 v1, 0
	s_nop 1
	s_add_u32 s16, s16, 0x23500
	s_addc_u32 s17, s17, 0
	global_load_dword v1, v1, s[16:17] sc1
	s_waitcnt vmcnt(0)
	v_cmp_eq_u32_e32 vcc, v1, v2
	s_and_saveexec_b64 s[12:13], vcc
	s_cbranch_execz .LBB0_952
	v_readlane_b32 s20, v239, 1
	v_readlane_b32 s22, v239, 3
	v_readlane_b32 s23, v239, 4
	s_add_u32 s14, s22, 0x20200
	v_readlane_b32 s21, v239, 2
	s_addc_u32 s15, s23, 0
	s_mov_b32 s2, 1
	s_mov_b64 s[18:19], 0
	v_mov_b32_e32 v1, 0
	s_branch .LBB0_943
